# 5 grid barriers (P1-P2, P5-P7, P7-P8, P8-P10, P12-P13) made XCD-local behind a runtime placement check
# speedup vs baseline: 1.0084x; 1.0084x over previous
_Z8yoco_fwd4Args:
	s_load_dwordx2 s[52:53], s[0:1], 0x88
	s_add_u32 s16, s0, 0x88
	v_and_b32_e32 v192, 0x3ff, v0
	s_addc_u32 s17, s1, 0
	v_cmp_gt_u32_e32 vcc, 16, v192
	s_and_saveexec_b64 s[4:5], vcc
	v_lshl_add_u32 v1, v192, 2, 0
	v_add_u32_e32 v1, 0x23fc0, v1
	v_mov_b32_e32 v2, 0
	ds_write_b32 v1, v2
	s_or_b64 exec, exec, s[4:5]
	s_mov_b64 s[6:7], s[0:1]
	s_waitcnt lgkmcnt(0)
	s_barrier
	s_getreg_b32 s3, hwreg(HW_REG_XCC_ID, 0, 4)
	v_cmp_eq_u32_e64 s[44:45], 0, v192
	s_and_saveexec_b64 s[4:5], s[44:45]
	s_cbranch_execz .LBB0_5
	s_mov_b64 s[8:9], exec
	v_mbcnt_lo_u32_b32 v1, s8, 0
	v_mbcnt_hi_u32_b32 v1, s9, v1
	v_cmp_eq_u32_e32 vcc, 0, v1
	s_and_b64 s[10:11], exec, vcc
	s_mov_b64 exec, s[10:11]
	s_cbranch_execz .LBB0_5
	s_load_dwordx2 s[98:99], s[0:1], 0x80
	v_mov_b32_e32 v3, s3
	v_mov_b32_e32 v6, s2
	v_add_u32_e32 v4, 1, v3
	v_sub_u32_e32 v5, 16, v3
	v_and_b32_e32 v6, 7, v6
	v_lshlrev_b32_e32 v6, 8, v6
	s_waitcnt lgkmcnt(0)
	global_atomic_umax v6, v4, s[98:99]
	global_atomic_umax v6, v5, s[98:99] offset:2048
	s_load_dwordx2 s[6:7], s[6:7], 0x80
	s_lshl_b32 s3, s3, 8
	s_and_b32 s3, s3, 0xf00
	v_mov_b32_e32 v1, 0x4000
	s_waitcnt lgkmcnt(0)
	s_add_u32 s6, s6, s3
	s_addc_u32 s7, s7, 0
	s_bcnt1_i32_b64 s3, s[8:9]
	v_mov_b32_e32 v2, s3
	global_atomic_add v1, v2, s[6:7] offset:1024

.LBB0_217:
	s_or_b64 exec, exec, s[4:5]
	s_cmpk_lt_i32 s2, 0x300
	s_cselect_b64 s[6:7], -1, 0
	s_mov_b64 s[4:5], s[0:1]
	s_waitcnt vmcnt(14)
	v_mov_b32_e32 v8, v192
	s_waitcnt lgkmcnt(0)
	s_barrier
	s_waitcnt vmcnt(0)
	s_load_dwordx2 s[98:99], s[0:1], 0x80
	v_and_b32_e32 v0, 7, v192
	v_lshlrev_b32_e32 v0, 8, v0
	s_waitcnt lgkmcnt(0)
	global_load_dword v1, v0, s[98:99] sc1
	global_load_dword v2, v0, s[98:99] offset:2048 sc1
	s_waitcnt vmcnt(0)
	v_add_u32_e32 v1, v1, v2
	v_cmp_ne_u32_e32 vcc, 17, v1
	s_nop 3
	s_cmp_eq_u64 vcc, 0
	s_cselect_b32 s99, 1, 0
	s_ashr_i32 s47, s52, 31
	s_ashr_i32 s76, s2, 31
	v_writelane_b32 v250, s6, 0
	v_readfirstlane_b32 s13, v8
	s_and_b64 vcc, exec, s[6:7]
	v_writelane_b32 v250, s7, 1
	s_cbranch_vccz .LBB0_233
	v_lshlrev_b32_e32 v0, 4, v8
	v_add_u32_e32 v1, 0x2000, v0
	v_ashrrev_i32_e32 v2, 31, v1
	v_lshrrev_b32_e32 v2, 22, v2
	v_add_u32_e32 v2, v1, v2
	v_ashrrev_i32_e32 v9, 10, v2
	v_mul_i32_i24_e32 v2, 0x400, v9
	v_sub_u32_e32 v1, v1, v2
	v_lshrrev_b32_e32 v2, 4, v1
	v_bitop3_b32 v1, v2, v1, 32 bitop3:0x6c
	v_ashrrev_i32_e32 v2, 31, v1
	v_lshrrev_b32_e32 v2, 26, v2
	v_add_u32_e32 v2, v1, v2
	v_lshlrev_b32_e32 v3, 3, v9
	s_waitcnt vmcnt(13)
	v_ashrrev_i32_e32 v10, 6, v2
	v_and_b32_e32 v3, -16, v3
	v_add_u32_e32 v3, v10, v3
	v_and_b32_e32 v4, 3, v10
	s_mov_b32 s6, 0xfffe0
	v_lshrrev_b32_e32 v5, 2, v3
	v_lshlrev_b32_e32 v6, 1, v3
	v_and_b32_e32 v2, 0xc0, v2
	v_and_or_b32 v4, v3, s6, v4
	v_and_b32_e32 v5, 4, v5
	v_and_b32_e32 v6, 24, v6
	v_sub_u32_e32 v1, v1, v2
	v_mov_b32_e32 v2, 1
	v_or3_b32 v4, v4, v5, v6
	v_lshlrev_b32_e32 v5, 5, v9
	v_ashrrev_i16_sdwa v1, v2, sext(v1) dst_sel:DWORD dst_unused:UNUSED_PAD src0_sel:DWORD src1_sel:BYTE_0
	v_and_b32_e32 v5, 32, v5
	v_bfe_i32 v11, v1, 0, 16
	v_add_lshl_u32 v1, v5, v11, 1
	v_lshl_add_u32 v128, v4, 12, v1
	v_lshl_add_u32 v130, v3, 12, v1
	v_bfe_i32 v1, v8, 27, 1
	v_lshrrev_b32_e32 v1, 22, v1
	v_add_u32_e32 v1, v0, v1
	v_and_b32_e32 v1, 0xfffffc00, v1
	s_load_dwordx2 s[4:5], s[4:5], 0x80
	v_sub_u32_e32 v0, v0, v1
	v_lshrrev_b32_e32 v1, 4, v0
	v_ashrrev_i32_e32 v3, 31, v8
	v_bitop3_b32 v0, v1, v0, 32 bitop3:0x6c
	v_lshrrev_b32_e32 v3, 26, v3
	v_ashrrev_i32_e32 v1, 31, v0
	v_add_u32_e32 v3, v8, v3
	v_lshrrev_b32_e32 v1, 26, v1
	v_ashrrev_i32_e32 v13, 6, v3
	s_waitcnt lgkmcnt(0)
	s_add_u32 s30, s4, 0xc600000
	v_add_u32_e32 v1, v0, v1
	v_lshlrev_b32_e32 v3, 3, v13
	s_addc_u32 s31, s5, 0
	v_ashrrev_i32_e32 v12, 6, v1
	v_and_b32_e32 v3, -16, v3
	s_add_u32 s34, s4, 0x100000
	v_add_u32_e32 v3, v12, v3
	v_and_b32_e32 v4, 3, v12
	s_addc_u32 s35, s5, 0
	v_and_or_b32 v4, v3, s6, v4
	s_lshr_b32 s6, s76, 29
	s_add_i32 s6, s2, s6
	s_ashr_i32 s10, s13, 6
	s_ashr_i32 s7, s6, 3
	s_and_b32 s6, s6, -8
	s_ashr_i32 s14, s13, 8
	s_lshl_b32 s36, s10, 10
	s_sub_i32 s6, s2, s6
	s_cmp_lt_i32 s6, 0
	s_movk_i32 s37, 0x61
	s_cselect_b32 s8, s37, 0x60
	s_mul_i32 s6, s6, s8
	s_add_i32 s6, s6, s7
	s_mul_hi_i32 s7, s6, 0x2aaaaaab
	s_lshr_b32 s8, s7, 31
	s_ashr_i32 s7, s7, 4
	s_add_i32 s7, s7, s8
	s_lshl_b32 s8, s7, 2
	s_mulk_i32 s7, 0x60
	s_sub_i32 s6, s6, s7
	s_bfe_i32 s7, s6, 0x80000
	s_bfe_u32 s7, s7, 0x2000d
	s_add_i32 s7, s6, s7
	s_bfe_i32 s9, s7, 0x80000
	s_and_b32 s7, s7, 0xfc
	s_sub_i32 s6, s6, s7
	s_sext_i32_i16 s9, s9
	s_sext_i32_i8 s6, s6
	v_lshrrev_b32_e32 v5, 2, v3
	v_lshlrev_b32_e32 v6, 1, v3
	v_and_b32_e32 v1, 0xc0, v1
	s_lshr_b32 s12, s9, 2
	s_add_i32 s22, s8, s6
	v_and_b32_e32 v5, 4, v5
	v_and_b32_e32 v6, 24, v6
	v_sub_u32_e32 v0, v0, v1
	s_ashr_i32 s23, s22, 31
	s_bfe_i64 s[8:9], s[12:13], 0x100000
	v_or3_b32 v4, v4, v5, v6
	v_lshlrev_b32_e32 v5, 5, v13
	v_ashrrev_i16_sdwa v0, v2, sext(v0) dst_sel:DWORD dst_unused:UNUSED_PAD src0_sel:DWORD src1_sel:BYTE_0
	s_lshl_b64 s[6:7], s[22:23], 20
	s_lshl_b64 s[8:9], s[8:9], 20
	v_and_b32_e32 v5, 32, v5
	s_waitcnt vmcnt(12)
	v_bfe_i32 v14, v0, 0, 16
	s_add_u32 s26, s34, s8
	v_add_lshl_u32 v0, v5, v14, 1
	s_addc_u32 s27, s35, s9
	s_add_i32 s23, s36, 0
	v_lshl_add_u32 v132, v4, 12, v0
	s_add_i32 m0, s23, 0x10000
	v_lshl_add_u32 v134, v3, 12, v0
	global_load_lds_dwordx4 v132, s[26:27]
	s_add_i32 m0, s23, 0x12000
	s_add_u32 s8, s26, 0x80000
	global_load_lds_dwordx4 v128, s[26:27]
	s_addc_u32 s9, s27, 0
	s_add_i32 m0, s23, 0x14000
	v_mov_b32_e32 v133, 0
	global_load_lds_dwordx4 v132, s[8:9]
	s_add_i32 m0, s23, 0x16000
	s_add_u32 s24, s30, s6
	s_addc_u32 s25, s31, s7
	s_add_i32 s38, s23, 0x2000
	global_load_lds_dwordx4 v128, s[8:9]
	s_mov_b32 m0, s23
	s_add_u32 s6, s24, 0x80000
	global_load_lds_dwordx4 v134, s[24:25]
	s_mov_b32 m0, s38
	s_addc_u32 s7, s25, 0
	s_add_i32 s39, s23, 0x4000
	global_load_lds_dwordx4 v130, s[24:25]
	s_mov_b32 m0, s39
	s_add_i32 s40, s23, 0x6000
	global_load_lds_dwordx4 v134, s[6:7]
	s_mov_b32 m0, s40
	v_mov_b32_e32 v129, v133
	global_load_lds_dwordx4 v130, s[6:7]
	v_mov_b32_e32 v135, v133
	v_mov_b32_e32 v131, v133
	s_cmp_eq_u32 s14, 1
	s_mov_b32 s41, 0
	v_lshl_add_u64 v[6:7], s[26:27], 0, v[132:133]
	v_lshl_add_u64 v[4:5], s[26:27], 0, v[128:129]
	v_lshl_add_u64 v[0:1], s[24:25], 0, v[134:135]
	s_cselect_b64 s[6:7], -1, 0
	s_cmp_lg_u32 s14, 1
	v_lshl_add_u64 v[2:3], s[24:25], 0, v[130:131]
	s_cbranch_scc1 .LBB0_220
	s_barrier

.LBB0_265:
	s_andn2_saveexec_b64 s[10:11], s[10:11]
	s_cbranch_execz .LBB0_285
	s_waitcnt lgkmcnt(0)
	s_cmp_lg_u32 s99, 0
	s_cbranch_scc1 .Lxcd_local_0
	s_mov_b64 s[12:13], exec
	buffer_wbl2 sc1
	s_waitcnt lgkmcnt(0)
	s_waitcnt vmcnt(0)
	v_mbcnt_lo_u32_b32 v1, s12, 0
	v_mbcnt_hi_u32_b32 v1, s13, v1
	v_cmp_eq_u32_e32 vcc, 0, v1
	s_and_saveexec_b64 s[14:15], vcc
	s_cbranch_execz .LBB0_268
	s_bcnt1_i32_b64 s12, s[12:13]
	v_mov_b32_e32 v2, 0x7000
	v_mov_b32_e32 v3, s12
	global_atomic_add v2, v2, v3, s[6:7] offset:1024 sc0

.Lxcd_local_0:
	s_mov_b64 s[6:7], exec
	v_mbcnt_lo_u32_b32 v0, s6, 0
	v_mbcnt_hi_u32_b32 v0, s7, v0
	v_cmp_eq_u32_e32 vcc, 0, v0
	s_waitcnt vmcnt(0)
	buffer_inv sc1
	s_and_saveexec_b64 s[12:13], vcc
	s_cbranch_execz .LBB0_284
	s_bcnt1_i32_b64 s6, s[6:7]
	v_mov_b32_e32 v0, 0x2000
	v_mov_b32_e32 v1, s6
	global_atomic_add v0, v1, s[8:9] offset:1024

.LBB0_644:
	s_andn2_saveexec_b64 s[12:13], s[12:13]
	s_cbranch_execz .LBB0_664
	s_waitcnt lgkmcnt(0)
	s_cmp_lg_u32 s99, 0
	s_cbranch_scc1 .Lxcd_local_1
	s_mov_b64 s[12:13], exec
	buffer_wbl2 sc1
	s_waitcnt lgkmcnt(0)
	s_waitcnt vmcnt(0)
	v_mbcnt_lo_u32_b32 v1, s12, 0
	v_mbcnt_hi_u32_b32 v1, s13, v1
	v_cmp_eq_u32_e32 vcc, 0, v1
	s_and_saveexec_b64 s[14:15], vcc
	s_cbranch_execz .LBB0_647
	s_bcnt1_i32_b64 s12, s[12:13]
	v_mov_b32_e32 v2, 0x7000
	v_mov_b32_e32 v3, s12
	global_atomic_add v2, v2, v3, s[8:9] offset:1024 sc0

.Lxcd_local_1:
	s_mov_b64 s[8:9], exec
	v_mbcnt_lo_u32_b32 v0, s8, 0
	v_mbcnt_hi_u32_b32 v0, s9, v0
	v_cmp_eq_u32_e32 vcc, 0, v0
	s_waitcnt vmcnt(0)
	buffer_inv sc1
	s_and_saveexec_b64 s[12:13], vcc
	s_cbranch_execz .LBB0_663
	s_bcnt1_i32_b64 s8, s[8:9]
	v_mov_b32_e32 v0, 0x2000
	v_mov_b32_e32 v1, s8
	global_atomic_add v0, v1, s[10:11] offset:1024

.LBB0_1144:
	s_andn2_saveexec_b64 s[12:13], s[12:13]
	s_cbranch_execz .LBB0_1164
	s_waitcnt lgkmcnt(0)
	s_cmp_lg_u32 s99, 0
	s_cbranch_scc1 .Lxcd_local_2
	s_mov_b64 s[12:13], exec
	buffer_wbl2 sc1
	s_waitcnt lgkmcnt(0)
	s_waitcnt vmcnt(0)
	v_mbcnt_lo_u32_b32 v1, s12, 0
	v_mbcnt_hi_u32_b32 v1, s13, v1
	v_cmp_eq_u32_e32 vcc, 0, v1
	s_and_saveexec_b64 s[16:17], vcc
	s_cbranch_execz .LBB0_1147
	s_bcnt1_i32_b64 s12, s[12:13]
	v_mov_b32_e32 v2, 0x7000
	v_mov_b32_e32 v3, s12
	global_atomic_add v2, v2, v3, s[8:9] offset:1024 sc0

	.amdhsa_kernel _Z8yoco_fwd4Args
		.amdhsa_group_segment_fixed_size 0
		.amdhsa_private_segment_fixed_size 0
		.amdhsa_kernarg_size 392
		.amdhsa_user_sgpr_count 2
		.amdhsa_user_sgpr_dispatch_ptr 0
		.amdhsa_user_sgpr_queue_ptr 0
		.amdhsa_user_sgpr_kernarg_segment_ptr 1
		.amdhsa_user_sgpr_dispatch_id 0
		.amdhsa_user_sgpr_kernarg_preload_length 0
		.amdhsa_user_sgpr_kernarg_preload_offset 0
		.amdhsa_user_sgpr_private_segment_size 0
		.amdhsa_uses_dynamic_stack 0
		.amdhsa_enable_private_segment 0
		.amdhsa_system_sgpr_workgroup_id_x 1
		.amdhsa_system_sgpr_workgroup_id_y 0
		.amdhsa_system_sgpr_workgroup_id_z 0
		.amdhsa_system_sgpr_workgroup_info 0
		.amdhsa_system_vgpr_workitem_id 2
		.amdhsa_next_free_vgpr 251
		.amdhsa_next_free_sgpr 100
		.amdhsa_accum_offset 252
		.amdhsa_reserve_vcc 1
		.amdhsa_float_round_mode_32 0
		.amdhsa_float_round_mode_16_64 0
		.amdhsa_float_denorm_mode_32 3
		.amdhsa_float_denorm_mode_16_64 3
		.amdhsa_dx10_clamp 1
		.amdhsa_ieee_mode 1
		.amdhsa_fp16_overflow 0
		.amdhsa_tg_split 0
		.amdhsa_exception_fp_ieee_invalid_op 0
		.amdhsa_exception_fp_denorm_src 0
		.amdhsa_exception_fp_ieee_div_zero 0
		.amdhsa_exception_fp_ieee_overflow 0
		.amdhsa_exception_fp_ieee_underflow 0
		.amdhsa_exception_fp_ieee_inexact 0
		.amdhsa_exception_int_div_zero 0
	.end_amdhsa_kernel

amdhsa.kernels:
  - .agpr_count:     0
    .args:
      - .offset:         0
        .size:           136
        .value_kind:     by_value
      - .offset:         136
        .size:           4
        .value_kind:     hidden_block_count_x
      - .offset:         140
        .size:           4
        .value_kind:     hidden_block_count_y
      - .offset:         144
        .size:           4
        .value_kind:     hidden_block_count_z
      - .offset:         148
        .size:           2
        .value_kind:     hidden_group_size_x
      - .offset:         150
        .size:           2
        .value_kind:     hidden_group_size_y
      - .offset:         152
        .size:           2
        .value_kind:     hidden_group_size_z
      - .offset:         154
        .size:           2
        .value_kind:     hidden_remainder_x
      - .offset:         156
        .size:           2
        .value_kind:     hidden_remainder_y
      - .offset:         158
        .size:           2
        .value_kind:     hidden_remainder_z
      - .offset:         176
        .size:           8
        .value_kind:     hidden_global_offset_x
      - .offset:         184
        .size:           8
        .value_kind:     hidden_global_offset_y
      - .offset:         192
        .size:           8
        .value_kind:     hidden_global_offset_z
      - .offset:         200
        .size:           2
        .value_kind:     hidden_grid_dims
      - .offset:         224
        .size:           8
        .value_kind:     hidden_multigrid_sync_arg
      - .offset:         256
        .size:           4
        .value_kind:     hidden_dynamic_lds_size
    .group_segment_fixed_size: 0
    .kernarg_segment_align: 8
    .kernarg_segment_size: 392
    .language:       OpenCL C
    .language_version:
      - 2
      - 0
    .max_flat_workgroup_size: 512
    .name:           _Z8yoco_fwd4Args
    .private_segment_fixed_size: 0
    .sgpr_count:     106
    .sgpr_spill_count: 4
    .symbol:         _Z8yoco_fwd4Args.kd
    .uniform_work_group_size: 1
    .uses_dynamic_stack: false
    .vgpr_count:     251
    .vgpr_spill_count: 0
    .wavefront_size: 64
